# EpiGate2 (phase 8 epilogue): T/gate loads software-pipelined two row-groups ahead instead of eight serialized load-wait-store blocks
# baseline (speedup 1.0000x reference)
; __device__ __forceinline__ unsigned pk2(float lo, float hi) { f32x2 v = {lo, hi}; bf16x2_t b = __builtin_convertvector(v, bf16x2_t); return __builtin_bit_cast(unsigned, b); }
; __device__ __forceinline__ float bflo(unsigned w) { return __uint_as_float(w << 16); }
; __device__ __forceinline__ float bfhi(unsigned w) { return __uint_as_float(w & 0xffff0000u); }
;     __device__ __forceinline__ void operator()(const f32x4 (&acc)[2][2][4][2], const Unit& u, int wr, int wc, int fr, int fq) const {
;         const int col0 = u.pn * 256 + wc * 32 + 8 * fq;
; #pragma unroll
;         for (int ai = 0; ai < 2; ++ai)
; #pragma unroll
;             for (int m = 0; m < 4; ++m) {
;                 const int row = u.pm * 256 + ai * 128 + wr * 64 + m * 16 + fr;
;                 if (row < MR) {
; #pragma unroll
;                     for (int bj = 0; bj < 2; ++bj) {
;                         const u32x4 gv = *(const u32x4*)(GATE + (size_t)row * 2048 + 1024 + col0 + bj * 128);
;                         const u32x4 tv = *(const u32x4*)(T + (size_t)row * DM + col0 + bj * 128);
;                         f32x4 a = (f32x4){bflo(tv.x), bfhi(tv.x), bflo(tv.y), bfhi(tv.y)}, b = (f32x4){bflo(tv.z), bfhi(tv.z), bflo(tv.w), bfhi(tv.w)};
;                         const f32x4 x = acc[ai][bj][m][0], y = acc[ai][bj][m][1];
;                         a[0] += x[0] * bflo(gv.x); a[1] += x[1] * bfhi(gv.x); a[2] += x[2] * bflo(gv.y); a[3] += x[3] * bfhi(gv.y);
;                         b[0] += y[0] * bflo(gv.z); b[1] += y[1] * bfhi(gv.z); b[2] += y[2] * bflo(gv.w); b[3] += y[3] * bfhi(gv.w);
;                         u32x4 w; w.x = pk2(a[0], a[1]); w.y = pk2(a[2], a[3]); w.z = pk2(b[0], b[1]); w.w = pk2(b[2], b[3]);
;                         *(u32x4*)(MG + (size_t)row * DM + col0 + bj * 128) = w;
;                     }
;                 }
;                 asm volatile("" ::: "memory");
;             }
;     }
.LBB0_2028:
	v_lshl_or_b32 v144, s26, 8, v150
	v_lshl_add_u32 v146, s40, 8, v148
	v_ashrrev_i32_e32 v145, 31, v144
	v_cmp_gt_i32_e32 vcc, s61, v146
	v_lshlrev_b64 v[144:145], 1, v[144:145]
	v_mov_b32_e32 v227, 0
	v_mov_b32_e32 v226, v146
	v_lshlrev_b32_e32 v226, 11, v226
	v_lshl_add_u64 v[228:229], s[8:9], 0, v[226:227]
	v_lshl_add_u64 v[228:229], v[228:229], 0, v[144:145]
	global_load_dwordx4 v[190:193], v[228:229], off
	global_load_dwordx4 v[198:201], v[228:229], off offset:256
	v_lshlrev_b32_e32 v226, 1, v226
	v_lshl_add_u64 v[228:229], s[10:11], 0, v[226:227]
	v_lshl_add_u64 v[228:229], v[228:229], 0, v[144:145]
	global_load_dwordx4 v[194:197], v[228:229], off offset:2048
	global_load_dwordx4 v[202:205], v[228:229], off offset:2304
	v_add_u32_e32 v226, 0x10, v146
	v_lshlrev_b32_e32 v226, 11, v226
	v_lshl_add_u64 v[228:229], s[8:9], 0, v[226:227]
	v_lshl_add_u64 v[228:229], v[228:229], 0, v[144:145]
	global_load_dwordx4 v[206:209], v[228:229], off
	global_load_dwordx4 v[214:217], v[228:229], off offset:256
	v_lshlrev_b32_e32 v226, 1, v226
	v_lshl_add_u64 v[228:229], s[10:11], 0, v[226:227]
	v_lshl_add_u64 v[228:229], v[228:229], 0, v[144:145]
	global_load_dwordx4 v[210:213], v[228:229], off offset:2048
	global_load_dwordx4 v[230:233], v[228:229], off offset:2304
	s_and_saveexec_b64 s[26:27], vcc
	s_cbranch_execz .LBB0_2030
	v_ashrrev_i32_e32 v147, 31, v146
	v_lshlrev_b64 v[154:155], 12, v[146:147]
	v_lshlrev_b64 v[170:171], 11, v[146:147]
	v_lshl_add_u64 v[158:159], s[10:11], 0, v[154:155]
	v_lshl_add_u64 v[154:155], s[8:9], 0, v[170:171]
	v_lshl_add_u64 v[162:163], v[154:155], 0, v[144:145]
	v_lshl_add_u64 v[166:167], v[158:159], 0, v[144:145]
	s_nop 0
	s_nop 0
	v_lshl_add_u64 v[170:171], s[12:13], 0, v[170:171]
	v_lshl_add_u64 v[170:171], v[170:171], 0, v[144:145]
	s_waitcnt vmcnt(4)
	v_mov_b32_e32 v154, v190
	v_mov_b32_e32 v155, v191
	v_mov_b32_e32 v156, v192
	v_mov_b32_e32 v157, v193
	v_mov_b32_e32 v158, v194
	v_mov_b32_e32 v159, v195
	v_mov_b32_e32 v160, v196
	v_mov_b32_e32 v161, v197
	v_mov_b32_e32 v162, v198
	v_mov_b32_e32 v163, v199
	v_mov_b32_e32 v164, v200
	v_mov_b32_e32 v165, v201
	v_mov_b32_e32 v166, v202
	v_mov_b32_e32 v167, v203
	v_mov_b32_e32 v168, v204
	v_mov_b32_e32 v169, v205
	v_lshlrev_b32_e32 v174, 16, v158
	v_lshlrev_b32_e32 v172, 16, v154
	v_and_b32_e32 v173, 0xffff0000, v154
	v_and_b32_e32 v175, 0xffff0000, v158
	v_lshlrev_b32_e32 v154, 16, v155
	v_and_b32_e32 v155, 0xffff0000, v155
	v_lshlrev_b32_e32 v158, 16, v159
	v_and_b32_e32 v159, 0xffff0000, v159
	v_lshlrev_b32_e32 v176, 16, v156
	v_and_b32_e32 v177, 0xffff0000, v156
	v_lshlrev_b32_e32 v178, 16, v160
	v_and_b32_e32 v179, 0xffff0000, v160
	v_lshlrev_b32_e32 v156, 16, v157
	v_and_b32_e32 v157, 0xffff0000, v157
	v_lshlrev_b32_e32 v160, 16, v161
	v_and_b32_e32 v161, 0xffff0000, v161
	v_lshlrev_b32_e32 v182, 16, v162
	v_and_b32_e32 v183, 0xffff0000, v162
	v_lshlrev_b32_e32 v184, 16, v166
	v_and_b32_e32 v185, 0xffff0000, v166
	v_lshlrev_b32_e32 v162, 16, v163
	v_and_b32_e32 v163, 0xffff0000, v163
	v_lshlrev_b32_e32 v166, 16, v167
	v_and_b32_e32 v167, 0xffff0000, v167
	v_lshlrev_b32_e32 v186, 16, v164
	v_and_b32_e32 v187, 0xffff0000, v164
	v_lshlrev_b32_e32 v188, 16, v168
	v_and_b32_e32 v189, 0xffff0000, v168
	v_lshlrev_b32_e32 v164, 16, v165
	v_and_b32_e32 v165, 0xffff0000, v165
	v_lshlrev_b32_e32 v168, 16, v169
	v_and_b32_e32 v169, 0xffff0000, v169
	v_pk_fma_f32 v[124:125], v[124:125], v[174:175], v[172:173]
	v_pk_fma_f32 v[126:127], v[126:127], v[158:159], v[154:155]
	v_pk_fma_f32 v[120:121], v[120:121], v[178:179], v[176:177]
	v_pk_fma_f32 v[122:123], v[122:123], v[160:161], v[156:157]
	v_pk_fma_f32 v[116:117], v[116:117], v[184:185], v[182:183]
	v_pk_fma_f32 v[118:119], v[118:119], v[166:167], v[162:163]
	v_pk_fma_f32 v[154:155], v[112:113], v[188:189], v[186:187]
	v_pk_fma_f32 v[156:157], v[114:115], v[168:169], v[164:165]
	v_cvt_pk_bf16_f32 v112, v124, v125
	v_cvt_pk_bf16_f32 v113, v126, v127
	v_cvt_pk_bf16_f32 v114, v120, v121
	v_cvt_pk_bf16_f32 v115, v122, v123
	v_cvt_pk_bf16_f32 v116, v116, v117
	v_cvt_pk_bf16_f32 v117, v118, v119
	v_cvt_pk_bf16_f32 v118, v154, v155
	v_cvt_pk_bf16_f32 v119, v156, v157
	global_store_dwordx4 v[170:171], v[112:115], off
	global_store_dwordx4 v[170:171], v[116:119], off offset:256
; __device__ __forceinline__ unsigned pk2(float lo, float hi) { f32x2 v = {lo, hi}; bf16x2_t b = __builtin_convertvector(v, bf16x2_t); return __builtin_bit_cast(unsigned, b); }
; __device__ __forceinline__ float bflo(unsigned w) { return __uint_as_float(w << 16); }
; __device__ __forceinline__ float bfhi(unsigned w) { return __uint_as_float(w & 0xffff0000u); }
;     __device__ __forceinline__ void operator()(const f32x4 (&acc)[2][2][4][2], const Unit& u, int wr, int wc, int fr, int fq) const {
;         const int col0 = u.pn * 256 + wc * 32 + 8 * fq;
; #pragma unroll
;         for (int ai = 0; ai < 2; ++ai)
; #pragma unroll
;             for (int m = 0; m < 4; ++m) {
;                 const int row = u.pm * 256 + ai * 128 + wr * 64 + m * 16 + fr;
;                 if (row < MR) {
; #pragma unroll
;                     for (int bj = 0; bj < 2; ++bj) {
;                         const u32x4 gv = *(const u32x4*)(GATE + (size_t)row * 2048 + 1024 + col0 + bj * 128);
;                         const u32x4 tv = *(const u32x4*)(T + (size_t)row * DM + col0 + bj * 128);
;                         f32x4 a = (f32x4){bflo(tv.x), bfhi(tv.x), bflo(tv.y), bfhi(tv.y)}, b = (f32x4){bflo(tv.z), bfhi(tv.z), bflo(tv.w), bfhi(tv.w)};
;                         const f32x4 x = acc[ai][bj][m][0], y = acc[ai][bj][m][1];
;                         a[0] += x[0] * bflo(gv.x); a[1] += x[1] * bfhi(gv.x); a[2] += x[2] * bflo(gv.y); a[3] += x[3] * bfhi(gv.y);
;                         b[0] += y[0] * bflo(gv.z); b[1] += y[1] * bfhi(gv.z); b[2] += y[2] * bflo(gv.w); b[3] += y[3] * bfhi(gv.w);
;                         u32x4 w; w.x = pk2(a[0], a[1]); w.y = pk2(a[2], a[3]); w.z = pk2(b[0], b[1]); w.w = pk2(b[2], b[3]);
;                         *(u32x4*)(MG + (size_t)row * DM + col0 + bj * 128) = w;
;                     }
;                 }
;                 asm volatile("" ::: "memory");
;             }
;     }
.LBB0_2030:
	s_or_b64 exec, exec, s[26:27]
	v_add_u32_e32 v226, 0x20, v146
	v_lshlrev_b32_e32 v226, 11, v226
	v_lshl_add_u64 v[228:229], s[8:9], 0, v[226:227]
	v_lshl_add_u64 v[228:229], v[228:229], 0, v[144:145]
	global_load_dwordx4 v[190:193], v[228:229], off
	global_load_dwordx4 v[198:201], v[228:229], off offset:256
	v_lshlrev_b32_e32 v226, 1, v226
	v_lshl_add_u64 v[228:229], s[10:11], 0, v[226:227]
	v_lshl_add_u64 v[228:229], v[228:229], 0, v[144:145]
	global_load_dwordx4 v[194:197], v[228:229], off offset:2048
	global_load_dwordx4 v[202:205], v[228:229], off offset:2304
	v_or_b32_e32 v112, 16, v146
	v_cmp_gt_i32_e32 vcc, s61, v112
	s_and_saveexec_b64 s[26:27], vcc
	s_cbranch_execz .LBB0_2032
	v_ashrrev_i32_e32 v113, 31, v112
	v_lshlrev_b64 v[154:155], 11, v[112:113]
	v_lshlrev_b64 v[114:115], 12, v[112:113]
	v_lshl_add_u64 v[112:113], s[8:9], 0, v[154:155]
	v_lshl_add_u64 v[116:117], s[10:11], 0, v[114:115]
	v_lshl_add_u64 v[120:121], v[112:113], 0, v[144:145]
	v_lshl_add_u64 v[124:125], v[116:117], 0, v[144:145]
	s_nop 0
	s_nop 0
	v_lshl_add_u64 v[154:155], s[12:13], 0, v[154:155]
	v_lshl_add_u64 v[154:155], v[154:155], 0, v[144:145]
	s_waitcnt vmcnt(6)
	v_mov_b32_e32 v112, v206
	v_mov_b32_e32 v113, v207
	v_mov_b32_e32 v114, v208
	v_mov_b32_e32 v115, v209
	v_mov_b32_e32 v116, v210
	v_mov_b32_e32 v117, v211
	v_mov_b32_e32 v118, v212
	v_mov_b32_e32 v119, v213
	v_mov_b32_e32 v120, v214
	v_mov_b32_e32 v121, v215
	v_mov_b32_e32 v122, v216
	v_mov_b32_e32 v123, v217
	v_mov_b32_e32 v124, v230
	v_mov_b32_e32 v125, v231
	v_mov_b32_e32 v126, v232
	v_mov_b32_e32 v127, v233
	v_lshlrev_b32_e32 v158, 16, v116
	v_lshlrev_b32_e32 v156, 16, v112
	v_and_b32_e32 v157, 0xffff0000, v112
	v_and_b32_e32 v159, 0xffff0000, v116
	v_lshlrev_b32_e32 v112, 16, v113
	v_and_b32_e32 v113, 0xffff0000, v113
	v_lshlrev_b32_e32 v116, 16, v117
	v_and_b32_e32 v117, 0xffff0000, v117
	v_lshlrev_b32_e32 v160, 16, v114
	v_and_b32_e32 v161, 0xffff0000, v114
	v_lshlrev_b32_e32 v162, 16, v118
	v_and_b32_e32 v163, 0xffff0000, v118
	v_lshlrev_b32_e32 v114, 16, v115
	v_and_b32_e32 v115, 0xffff0000, v115
	v_lshlrev_b32_e32 v118, 16, v119
	v_and_b32_e32 v119, 0xffff0000, v119
	v_lshlrev_b32_e32 v164, 16, v120
	v_and_b32_e32 v165, 0xffff0000, v120
	v_lshlrev_b32_e32 v166, 16, v124
	v_and_b32_e32 v167, 0xffff0000, v124
	v_lshlrev_b32_e32 v120, 16, v121
	v_and_b32_e32 v121, 0xffff0000, v121
	v_lshlrev_b32_e32 v124, 16, v125
	v_and_b32_e32 v125, 0xffff0000, v125
	v_lshlrev_b32_e32 v168, 16, v122
	v_and_b32_e32 v169, 0xffff0000, v122
	v_lshlrev_b32_e32 v170, 16, v126
	v_and_b32_e32 v171, 0xffff0000, v126
	v_lshlrev_b32_e32 v122, 16, v123
	v_and_b32_e32 v123, 0xffff0000, v123
	v_lshlrev_b32_e32 v126, 16, v127
	v_and_b32_e32 v127, 0xffff0000, v127
	v_pk_fma_f32 v[108:109], v[108:109], v[158:159], v[156:157]
	v_pk_fma_f32 v[110:111], v[110:111], v[116:117], v[112:113]
	v_pk_fma_f32 v[104:105], v[104:105], v[162:163], v[160:161]
	v_pk_fma_f32 v[106:107], v[106:107], v[118:119], v[114:115]
	v_pk_fma_f32 v[100:101], v[100:101], v[166:167], v[164:165]
	v_pk_fma_f32 v[102:103], v[102:103], v[124:125], v[120:121]
	v_pk_fma_f32 v[112:113], v[96:97], v[170:171], v[168:169]
	v_pk_fma_f32 v[114:115], v[98:99], v[126:127], v[122:123]
	v_cvt_pk_bf16_f32 v96, v108, v109
	v_cvt_pk_bf16_f32 v97, v110, v111
	v_cvt_pk_bf16_f32 v98, v104, v105
	v_cvt_pk_bf16_f32 v99, v106, v107
	v_cvt_pk_bf16_f32 v100, v100, v101
	v_cvt_pk_bf16_f32 v101, v102, v103
	v_cvt_pk_bf16_f32 v102, v112, v113
	v_cvt_pk_bf16_f32 v103, v114, v115
	global_store_dwordx4 v[154:155], v[96:99], off
	global_store_dwordx4 v[154:155], v[100:103], off offset:256
.LBB0_2032:
	s_or_b64 exec, exec, s[26:27]
	v_add_u32_e32 v226, 0x30, v146
	v_lshlrev_b32_e32 v226, 11, v226
	v_lshl_add_u64 v[228:229], s[8:9], 0, v[226:227]
	v_lshl_add_u64 v[228:229], v[228:229], 0, v[144:145]
	global_load_dwordx4 v[206:209], v[228:229], off
	global_load_dwordx4 v[214:217], v[228:229], off offset:256
	v_lshlrev_b32_e32 v226, 1, v226
	v_lshl_add_u64 v[228:229], s[10:11], 0, v[226:227]
	v_lshl_add_u64 v[228:229], v[228:229], 0, v[144:145]
	global_load_dwordx4 v[210:213], v[228:229], off offset:2048
	global_load_dwordx4 v[230:233], v[228:229], off offset:2304
	v_or_b32_e32 v96, 32, v146
	v_cmp_gt_i32_e32 vcc, s61, v96
	s_and_saveexec_b64 s[26:27], vcc
	s_cbranch_execz .LBB0_2034
; __device__ __forceinline__ unsigned pk2(float lo, float hi) { f32x2 v = {lo, hi}; bf16x2_t b = __builtin_convertvector(v, bf16x2_t); return __builtin_bit_cast(unsigned, b); }
; __device__ __forceinline__ float bflo(unsigned w) { return __uint_as_float(w << 16); }
; __device__ __forceinline__ float bfhi(unsigned w) { return __uint_as_float(w & 0xffff0000u); }
;     __device__ __forceinline__ void operator()(const f32x4 (&acc)[2][2][4][2], const Unit& u, int wr, int wc, int fr, int fq) const {
;         const int col0 = u.pn * 256 + wc * 32 + 8 * fq;
; #pragma unroll
;         for (int ai = 0; ai < 2; ++ai)
; #pragma unroll
;             for (int m = 0; m < 4; ++m) {
;                 const int row = u.pm * 256 + ai * 128 + wr * 64 + m * 16 + fr;
;                 if (row < MR) {
; #pragma unroll
;                     for (int bj = 0; bj < 2; ++bj) {
;                         const u32x4 gv = *(const u32x4*)(GATE + (size_t)row * 2048 + 1024 + col0 + bj * 128);
;                         const u32x4 tv = *(const u32x4*)(T + (size_t)row * DM + col0 + bj * 128);
;                         f32x4 a = (f32x4){bflo(tv.x), bfhi(tv.x), bflo(tv.y), bfhi(tv.y)}, b = (f32x4){bflo(tv.z), bfhi(tv.z), bflo(tv.w), bfhi(tv.w)};
;                         const f32x4 x = acc[ai][bj][m][0], y = acc[ai][bj][m][1];
;                         a[0] += x[0] * bflo(gv.x); a[1] += x[1] * bfhi(gv.x); a[2] += x[2] * bflo(gv.y); a[3] += x[3] * bfhi(gv.y);
;                         b[0] += y[0] * bflo(gv.z); b[1] += y[1] * bfhi(gv.z); b[2] += y[2] * bflo(gv.w); b[3] += y[3] * bfhi(gv.w);
;                         u32x4 w; w.x = pk2(a[0], a[1]); w.y = pk2(a[2], a[3]); w.z = pk2(b[0], b[1]); w.w = pk2(b[2], b[3]);
;                         *(u32x4*)(MG + (size_t)row * DM + col0 + bj * 128) = w;
;                     }
;                 }
;                 asm volatile("" ::: "memory");
;             }
;     }
	v_ashrrev_i32_e32 v97, 31, v96
	v_lshlrev_b64 v[112:113], 11, v[96:97]
	v_lshlrev_b64 v[98:99], 12, v[96:97]
	v_lshl_add_u64 v[96:97], s[8:9], 0, v[112:113]
	v_lshl_add_u64 v[100:101], s[10:11], 0, v[98:99]
	v_lshl_add_u64 v[104:105], v[96:97], 0, v[144:145]
	v_lshl_add_u64 v[108:109], v[100:101], 0, v[144:145]
	s_nop 0
	s_nop 0
	v_lshl_add_u64 v[112:113], s[12:13], 0, v[112:113]
	v_lshl_add_u64 v[112:113], v[112:113], 0, v[144:145]
	s_waitcnt vmcnt(6)
	v_mov_b32_e32 v96, v190
	v_mov_b32_e32 v97, v191
	v_mov_b32_e32 v98, v192
	v_mov_b32_e32 v99, v193
	v_mov_b32_e32 v100, v194
	v_mov_b32_e32 v101, v195
	v_mov_b32_e32 v102, v196
	v_mov_b32_e32 v103, v197
	v_mov_b32_e32 v104, v198
	v_mov_b32_e32 v105, v199
	v_mov_b32_e32 v106, v200
	v_mov_b32_e32 v107, v201
	v_mov_b32_e32 v108, v202
	v_mov_b32_e32 v109, v203
	v_mov_b32_e32 v110, v204
	v_mov_b32_e32 v111, v205
	v_lshlrev_b32_e32 v116, 16, v100
	v_lshlrev_b32_e32 v114, 16, v96
	v_and_b32_e32 v115, 0xffff0000, v96
	v_and_b32_e32 v117, 0xffff0000, v100
	v_lshlrev_b32_e32 v96, 16, v97
	v_and_b32_e32 v97, 0xffff0000, v97
	v_lshlrev_b32_e32 v100, 16, v101
	v_and_b32_e32 v101, 0xffff0000, v101
	v_lshlrev_b32_e32 v118, 16, v98
	v_and_b32_e32 v119, 0xffff0000, v98
	v_lshlrev_b32_e32 v120, 16, v102
	v_and_b32_e32 v121, 0xffff0000, v102
	v_lshlrev_b32_e32 v98, 16, v99
	v_and_b32_e32 v99, 0xffff0000, v99
	v_lshlrev_b32_e32 v102, 16, v103
	v_and_b32_e32 v103, 0xffff0000, v103
	v_lshlrev_b32_e32 v122, 16, v104
	v_and_b32_e32 v123, 0xffff0000, v104
	v_lshlrev_b32_e32 v124, 16, v108
	v_and_b32_e32 v125, 0xffff0000, v108
	v_lshlrev_b32_e32 v104, 16, v105
	v_and_b32_e32 v105, 0xffff0000, v105
	v_lshlrev_b32_e32 v108, 16, v109
	v_and_b32_e32 v109, 0xffff0000, v109
	v_lshlrev_b32_e32 v126, 16, v106
	v_and_b32_e32 v127, 0xffff0000, v106
	v_lshlrev_b32_e32 v154, 16, v110
	v_and_b32_e32 v155, 0xffff0000, v110
	v_lshlrev_b32_e32 v106, 16, v107
	v_and_b32_e32 v107, 0xffff0000, v107
	v_lshlrev_b32_e32 v110, 16, v111
	v_and_b32_e32 v111, 0xffff0000, v111
	v_pk_fma_f32 v[92:93], v[92:93], v[116:117], v[114:115]
	v_pk_fma_f32 v[94:95], v[94:95], v[100:101], v[96:97]
	v_pk_fma_f32 v[88:89], v[88:89], v[120:121], v[118:119]
	v_pk_fma_f32 v[90:91], v[90:91], v[102:103], v[98:99]
	v_pk_fma_f32 v[84:85], v[84:85], v[124:125], v[122:123]
	v_pk_fma_f32 v[86:87], v[86:87], v[108:109], v[104:105]
	v_pk_fma_f32 v[96:97], v[80:81], v[154:155], v[126:127]
	v_pk_fma_f32 v[98:99], v[82:83], v[110:111], v[106:107]
	v_cvt_pk_bf16_f32 v80, v92, v93
	v_cvt_pk_bf16_f32 v81, v94, v95
	v_cvt_pk_bf16_f32 v82, v88, v89
	v_cvt_pk_bf16_f32 v83, v90, v91
	v_cvt_pk_bf16_f32 v84, v84, v85
	v_cvt_pk_bf16_f32 v85, v86, v87
	v_cvt_pk_bf16_f32 v86, v96, v97
	v_cvt_pk_bf16_f32 v87, v98, v99
	global_store_dwordx4 v[112:113], v[80:83], off
	global_store_dwordx4 v[112:113], v[84:87], off offset:256
.LBB0_2034:
	s_or_b64 exec, exec, s[26:27]
	v_add_u32_e32 v226, 0x80, v146
	v_lshlrev_b32_e32 v226, 11, v226
	v_lshl_add_u64 v[228:229], s[8:9], 0, v[226:227]
	v_lshl_add_u64 v[228:229], v[228:229], 0, v[144:145]
	global_load_dwordx4 v[190:193], v[228:229], off
	global_load_dwordx4 v[198:201], v[228:229], off offset:256
	v_lshlrev_b32_e32 v226, 1, v226
	v_lshl_add_u64 v[228:229], s[10:11], 0, v[226:227]
	v_lshl_add_u64 v[228:229], v[228:229], 0, v[144:145]
	global_load_dwordx4 v[194:197], v[228:229], off offset:2048
	global_load_dwordx4 v[202:205], v[228:229], off offset:2304
	v_or_b32_e32 v80, 48, v146
	v_cmp_gt_i32_e32 vcc, s61, v80
	s_and_saveexec_b64 s[26:27], vcc
	s_cbranch_execz .LBB0_2036
	v_ashrrev_i32_e32 v81, 31, v80
	v_lshlrev_b64 v[96:97], 11, v[80:81]
	v_lshlrev_b64 v[82:83], 12, v[80:81]
	v_lshl_add_u64 v[80:81], s[8:9], 0, v[96:97]
	v_lshl_add_u64 v[84:85], s[10:11], 0, v[82:83]
	v_lshl_add_u64 v[88:89], v[80:81], 0, v[144:145]
	v_lshl_add_u64 v[92:93], v[84:85], 0, v[144:145]
	s_nop 0
	s_nop 0
	v_lshl_add_u64 v[96:97], s[12:13], 0, v[96:97]
	v_lshl_add_u64 v[96:97], v[96:97], 0, v[144:145]
	s_waitcnt vmcnt(6)
	v_mov_b32_e32 v80, v206
	v_mov_b32_e32 v81, v207
	v_mov_b32_e32 v82, v208
	v_mov_b32_e32 v83, v209
	v_mov_b32_e32 v84, v210
	v_mov_b32_e32 v85, v211
	v_mov_b32_e32 v86, v212
	v_mov_b32_e32 v87, v213
	v_mov_b32_e32 v88, v214
	v_mov_b32_e32 v89, v215
	v_mov_b32_e32 v90, v216
	v_mov_b32_e32 v91, v217
	v_mov_b32_e32 v92, v230
	v_mov_b32_e32 v93, v231
	v_mov_b32_e32 v94, v232
	v_mov_b32_e32 v95, v233
	v_lshlrev_b32_e32 v100, 16, v84
	v_lshlrev_b32_e32 v98, 16, v80
	v_and_b32_e32 v99, 0xffff0000, v80
	v_and_b32_e32 v101, 0xffff0000, v84
	v_lshlrev_b32_e32 v80, 16, v81
	v_and_b32_e32 v81, 0xffff0000, v81
	v_lshlrev_b32_e32 v84, 16, v85
	v_and_b32_e32 v85, 0xffff0000, v85
	v_lshlrev_b32_e32 v102, 16, v82
	v_and_b32_e32 v103, 0xffff0000, v82
	v_lshlrev_b32_e32 v104, 16, v86
	v_and_b32_e32 v105, 0xffff0000, v86
	v_lshlrev_b32_e32 v82, 16, v83
	v_and_b32_e32 v83, 0xffff0000, v83
	v_lshlrev_b32_e32 v86, 16, v87
	v_and_b32_e32 v87, 0xffff0000, v87
	v_lshlrev_b32_e32 v106, 16, v88
	v_and_b32_e32 v107, 0xffff0000, v88
	v_lshlrev_b32_e32 v108, 16, v92
	v_and_b32_e32 v109, 0xffff0000, v92
	v_lshlrev_b32_e32 v88, 16, v89
	v_and_b32_e32 v89, 0xffff0000, v89
	v_lshlrev_b32_e32 v92, 16, v93
	v_and_b32_e32 v93, 0xffff0000, v93
	v_lshlrev_b32_e32 v110, 16, v90
	v_and_b32_e32 v111, 0xffff0000, v90
	v_lshlrev_b32_e32 v112, 16, v94
	v_and_b32_e32 v113, 0xffff0000, v94
	v_lshlrev_b32_e32 v90, 16, v91
	v_and_b32_e32 v91, 0xffff0000, v91
	v_lshlrev_b32_e32 v94, 16, v95
	v_and_b32_e32 v95, 0xffff0000, v95
	v_pk_fma_f32 v[76:77], v[76:77], v[100:101], v[98:99]
	v_pk_fma_f32 v[78:79], v[78:79], v[84:85], v[80:81]
	v_pk_fma_f32 v[72:73], v[72:73], v[104:105], v[102:103]
	v_pk_fma_f32 v[74:75], v[74:75], v[86:87], v[82:83]
	v_pk_fma_f32 v[68:69], v[68:69], v[108:109], v[106:107]
	v_pk_fma_f32 v[70:71], v[70:71], v[92:93], v[88:89]
	v_pk_fma_f32 v[80:81], v[64:65], v[112:113], v[110:111]
	v_pk_fma_f32 v[82:83], v[66:67], v[94:95], v[90:91]
	v_cvt_pk_bf16_f32 v64, v76, v77
	v_cvt_pk_bf16_f32 v65, v78, v79
	v_cvt_pk_bf16_f32 v66, v72, v73
	v_cvt_pk_bf16_f32 v67, v74, v75
	v_cvt_pk_bf16_f32 v68, v68, v69
	v_cvt_pk_bf16_f32 v69, v70, v71
	v_cvt_pk_bf16_f32 v70, v80, v81
	v_cvt_pk_bf16_f32 v71, v82, v83
	global_store_dwordx4 v[96:97], v[64:67], off
	global_store_dwordx4 v[96:97], v[68:71], off offset:256
; __device__ __forceinline__ unsigned pk2(float lo, float hi) { f32x2 v = {lo, hi}; bf16x2_t b = __builtin_convertvector(v, bf16x2_t); return __builtin_bit_cast(unsigned, b); }
; __device__ __forceinline__ float bflo(unsigned w) { return __uint_as_float(w << 16); }
; __device__ __forceinline__ float bfhi(unsigned w) { return __uint_as_float(w & 0xffff0000u); }
;     __device__ __forceinline__ void operator()(const f32x4 (&acc)[2][2][4][2], const Unit& u, int wr, int wc, int fr, int fq) const {
;         const int col0 = u.pn * 256 + wc * 32 + 8 * fq;
; #pragma unroll
;         for (int ai = 0; ai < 2; ++ai)
; #pragma unroll
;             for (int m = 0; m < 4; ++m) {
;                 const int row = u.pm * 256 + ai * 128 + wr * 64 + m * 16 + fr;
;                 if (row < MR) {
; #pragma unroll
;                     for (int bj = 0; bj < 2; ++bj) {
;                         const u32x4 gv = *(const u32x4*)(GATE + (size_t)row * 2048 + 1024 + col0 + bj * 128);
;                         const u32x4 tv = *(const u32x4*)(T + (size_t)row * DM + col0 + bj * 128);
;                         f32x4 a = (f32x4){bflo(tv.x), bfhi(tv.x), bflo(tv.y), bfhi(tv.y)}, b = (f32x4){bflo(tv.z), bfhi(tv.z), bflo(tv.w), bfhi(tv.w)};
;                         const f32x4 x = acc[ai][bj][m][0], y = acc[ai][bj][m][1];
;                         a[0] += x[0] * bflo(gv.x); a[1] += x[1] * bfhi(gv.x); a[2] += x[2] * bflo(gv.y); a[3] += x[3] * bfhi(gv.y);
;                         b[0] += y[0] * bflo(gv.z); b[1] += y[1] * bfhi(gv.z); b[2] += y[2] * bflo(gv.w); b[3] += y[3] * bfhi(gv.w);
;                         u32x4 w; w.x = pk2(a[0], a[1]); w.y = pk2(a[2], a[3]); w.z = pk2(b[0], b[1]); w.w = pk2(b[2], b[3]);
;                         *(u32x4*)(MG + (size_t)row * DM + col0 + bj * 128) = w;
;                     }
;                 }
;                 asm volatile("" ::: "memory");
;             }
;     }
.LBB0_2036:
	s_or_b64 exec, exec, s[26:27]
	v_add_u32_e32 v226, 0x90, v146
	v_lshlrev_b32_e32 v226, 11, v226
	v_lshl_add_u64 v[228:229], s[8:9], 0, v[226:227]
	v_lshl_add_u64 v[228:229], v[228:229], 0, v[144:145]
	global_load_dwordx4 v[206:209], v[228:229], off
	global_load_dwordx4 v[214:217], v[228:229], off offset:256
	v_lshlrev_b32_e32 v226, 1, v226
	v_lshl_add_u64 v[228:229], s[10:11], 0, v[226:227]
	v_lshl_add_u64 v[228:229], v[228:229], 0, v[144:145]
	global_load_dwordx4 v[210:213], v[228:229], off offset:2048
	global_load_dwordx4 v[230:233], v[228:229], off offset:2304
	v_add_u32_e32 v64, 0x80, v146
	v_cmp_gt_i32_e32 vcc, s61, v64
	s_and_saveexec_b64 s[26:27], vcc
	s_cbranch_execz .LBB0_2038
	v_ashrrev_i32_e32 v65, 31, v64
	v_lshlrev_b64 v[80:81], 11, v[64:65]
	v_lshlrev_b64 v[66:67], 12, v[64:65]
	v_lshl_add_u64 v[64:65], s[8:9], 0, v[80:81]
	v_lshl_add_u64 v[68:69], s[10:11], 0, v[66:67]
	v_lshl_add_u64 v[72:73], v[64:65], 0, v[144:145]
	v_lshl_add_u64 v[76:77], v[68:69], 0, v[144:145]
	s_nop 0
	s_nop 0
	v_lshl_add_u64 v[80:81], s[12:13], 0, v[80:81]
	v_lshl_add_u64 v[80:81], v[80:81], 0, v[144:145]
	s_waitcnt vmcnt(6)
	v_mov_b32_e32 v64, v190
	v_mov_b32_e32 v65, v191
	v_mov_b32_e32 v66, v192
	v_mov_b32_e32 v67, v193
	v_mov_b32_e32 v68, v194
	v_mov_b32_e32 v69, v195
	v_mov_b32_e32 v70, v196
	v_mov_b32_e32 v71, v197
	v_mov_b32_e32 v72, v198
	v_mov_b32_e32 v73, v199
	v_mov_b32_e32 v74, v200
	v_mov_b32_e32 v75, v201
	v_mov_b32_e32 v76, v202
	v_mov_b32_e32 v77, v203
	v_mov_b32_e32 v78, v204
	v_mov_b32_e32 v79, v205
	v_lshlrev_b32_e32 v84, 16, v68
	v_lshlrev_b32_e32 v82, 16, v64
	v_and_b32_e32 v83, 0xffff0000, v64
	v_and_b32_e32 v85, 0xffff0000, v68
	v_lshlrev_b32_e32 v64, 16, v65
	v_and_b32_e32 v65, 0xffff0000, v65
	v_lshlrev_b32_e32 v68, 16, v69
	v_and_b32_e32 v69, 0xffff0000, v69
	v_lshlrev_b32_e32 v86, 16, v66
	v_and_b32_e32 v87, 0xffff0000, v66
	v_lshlrev_b32_e32 v88, 16, v70
	v_and_b32_e32 v89, 0xffff0000, v70
	v_lshlrev_b32_e32 v66, 16, v67
	v_and_b32_e32 v67, 0xffff0000, v67
	v_lshlrev_b32_e32 v70, 16, v71
	v_and_b32_e32 v71, 0xffff0000, v71
	v_lshlrev_b32_e32 v90, 16, v72
	v_and_b32_e32 v91, 0xffff0000, v72
	v_lshlrev_b32_e32 v92, 16, v76
	v_and_b32_e32 v93, 0xffff0000, v76
	v_lshlrev_b32_e32 v72, 16, v73
	v_and_b32_e32 v73, 0xffff0000, v73
	v_lshlrev_b32_e32 v76, 16, v77
	v_and_b32_e32 v77, 0xffff0000, v77
	v_lshlrev_b32_e32 v94, 16, v74
	v_and_b32_e32 v95, 0xffff0000, v74
	v_lshlrev_b32_e32 v96, 16, v78
	v_and_b32_e32 v97, 0xffff0000, v78
	v_lshlrev_b32_e32 v74, 16, v75
	v_and_b32_e32 v75, 0xffff0000, v75
	v_lshlrev_b32_e32 v78, 16, v79
	v_and_b32_e32 v79, 0xffff0000, v79
	v_pk_fma_f32 v[60:61], v[60:61], v[84:85], v[82:83]
	v_pk_fma_f32 v[62:63], v[62:63], v[68:69], v[64:65]
	v_pk_fma_f32 v[56:57], v[56:57], v[88:89], v[86:87]
	v_pk_fma_f32 v[58:59], v[58:59], v[70:71], v[66:67]
	v_pk_fma_f32 v[52:53], v[52:53], v[92:93], v[90:91]
	v_pk_fma_f32 v[54:55], v[54:55], v[76:77], v[72:73]
	v_pk_fma_f32 v[64:65], v[48:49], v[96:97], v[94:95]
	v_pk_fma_f32 v[66:67], v[50:51], v[78:79], v[74:75]
	v_cvt_pk_bf16_f32 v48, v60, v61
	v_cvt_pk_bf16_f32 v49, v62, v63
	v_cvt_pk_bf16_f32 v50, v56, v57
	v_cvt_pk_bf16_f32 v51, v58, v59
	v_cvt_pk_bf16_f32 v52, v52, v53
	v_cvt_pk_bf16_f32 v53, v54, v55
	v_cvt_pk_bf16_f32 v54, v64, v65
	v_cvt_pk_bf16_f32 v55, v66, v67
	global_store_dwordx4 v[80:81], v[48:51], off
	global_store_dwordx4 v[80:81], v[52:55], off offset:256
.LBB0_2038:
	s_or_b64 exec, exec, s[26:27]
	v_add_u32_e32 v226, 0xa0, v146
	v_lshlrev_b32_e32 v226, 11, v226
	v_lshl_add_u64 v[228:229], s[8:9], 0, v[226:227]
	v_lshl_add_u64 v[228:229], v[228:229], 0, v[144:145]
	global_load_dwordx4 v[190:193], v[228:229], off
	global_load_dwordx4 v[198:201], v[228:229], off offset:256
	v_lshlrev_b32_e32 v226, 1, v226
	v_lshl_add_u64 v[228:229], s[10:11], 0, v[226:227]
	v_lshl_add_u64 v[228:229], v[228:229], 0, v[144:145]
	global_load_dwordx4 v[194:197], v[228:229], off offset:2048
	global_load_dwordx4 v[202:205], v[228:229], off offset:2304
	v_add_u32_e32 v48, 0x90, v146
	v_cmp_gt_i32_e32 vcc, s61, v48
	s_and_saveexec_b64 s[26:27], vcc
	s_cbranch_execz .LBB0_2040
	v_ashrrev_i32_e32 v49, 31, v48
	v_lshlrev_b64 v[64:65], 11, v[48:49]
	v_lshlrev_b64 v[50:51], 12, v[48:49]
	v_lshl_add_u64 v[48:49], s[8:9], 0, v[64:65]
	v_lshl_add_u64 v[52:53], s[10:11], 0, v[50:51]
	v_lshl_add_u64 v[56:57], v[48:49], 0, v[144:145]
	v_lshl_add_u64 v[60:61], v[52:53], 0, v[144:145]
	s_nop 0
	s_nop 0
	v_lshl_add_u64 v[64:65], s[12:13], 0, v[64:65]
	v_lshl_add_u64 v[64:65], v[64:65], 0, v[144:145]
	s_waitcnt vmcnt(6)
	v_mov_b32_e32 v48, v206
	v_mov_b32_e32 v49, v207
	v_mov_b32_e32 v50, v208
	v_mov_b32_e32 v51, v209
	v_mov_b32_e32 v52, v210
	v_mov_b32_e32 v53, v211
	v_mov_b32_e32 v54, v212
	v_mov_b32_e32 v55, v213
	v_mov_b32_e32 v56, v214
	v_mov_b32_e32 v57, v215
	v_mov_b32_e32 v58, v216
	v_mov_b32_e32 v59, v217
	v_mov_b32_e32 v60, v230
	v_mov_b32_e32 v61, v231
	v_mov_b32_e32 v62, v232
	v_mov_b32_e32 v63, v233
	v_lshlrev_b32_e32 v68, 16, v52
	v_lshlrev_b32_e32 v66, 16, v48
	v_and_b32_e32 v67, 0xffff0000, v48
	v_and_b32_e32 v69, 0xffff0000, v52
	v_lshlrev_b32_e32 v48, 16, v49
	v_and_b32_e32 v49, 0xffff0000, v49
	v_lshlrev_b32_e32 v52, 16, v53
	v_and_b32_e32 v53, 0xffff0000, v53
	v_lshlrev_b32_e32 v70, 16, v50
	v_and_b32_e32 v71, 0xffff0000, v50
	v_lshlrev_b32_e32 v72, 16, v54
	v_and_b32_e32 v73, 0xffff0000, v54
	v_lshlrev_b32_e32 v50, 16, v51
	v_and_b32_e32 v51, 0xffff0000, v51
	v_lshlrev_b32_e32 v54, 16, v55
	v_and_b32_e32 v55, 0xffff0000, v55
	v_lshlrev_b32_e32 v74, 16, v56
	v_and_b32_e32 v75, 0xffff0000, v56
	v_lshlrev_b32_e32 v76, 16, v60
	v_and_b32_e32 v77, 0xffff0000, v60
	v_lshlrev_b32_e32 v56, 16, v57
	v_and_b32_e32 v57, 0xffff0000, v57
	v_lshlrev_b32_e32 v60, 16, v61
	v_and_b32_e32 v61, 0xffff0000, v61
	v_lshlrev_b32_e32 v78, 16, v58
	v_and_b32_e32 v79, 0xffff0000, v58
	v_lshlrev_b32_e32 v80, 16, v62
	v_and_b32_e32 v81, 0xffff0000, v62
	v_lshlrev_b32_e32 v58, 16, v59
	v_and_b32_e32 v59, 0xffff0000, v59
	v_lshlrev_b32_e32 v62, 16, v63
	v_and_b32_e32 v63, 0xffff0000, v63
	v_pk_fma_f32 v[44:45], v[44:45], v[68:69], v[66:67]
	v_pk_fma_f32 v[46:47], v[46:47], v[52:53], v[48:49]
	v_pk_fma_f32 v[40:41], v[40:41], v[72:73], v[70:71]
	v_pk_fma_f32 v[42:43], v[42:43], v[54:55], v[50:51]
	v_pk_fma_f32 v[36:37], v[36:37], v[76:77], v[74:75]
	v_pk_fma_f32 v[38:39], v[38:39], v[60:61], v[56:57]
	v_pk_fma_f32 v[48:49], v[32:33], v[80:81], v[78:79]
	v_pk_fma_f32 v[50:51], v[34:35], v[62:63], v[58:59]
	v_cvt_pk_bf16_f32 v32, v44, v45
	v_cvt_pk_bf16_f32 v33, v46, v47
	v_cvt_pk_bf16_f32 v34, v40, v41
	v_cvt_pk_bf16_f32 v35, v42, v43
	v_cvt_pk_bf16_f32 v36, v36, v37
	v_cvt_pk_bf16_f32 v37, v38, v39
	v_cvt_pk_bf16_f32 v38, v48, v49
	v_cvt_pk_bf16_f32 v39, v50, v51
	global_store_dwordx4 v[64:65], v[32:35], off
	global_store_dwordx4 v[64:65], v[36:39], off offset:256
; __device__ __forceinline__ unsigned pk2(float lo, float hi) { f32x2 v = {lo, hi}; bf16x2_t b = __builtin_convertvector(v, bf16x2_t); return __builtin_bit_cast(unsigned, b); }
; __device__ __forceinline__ float bflo(unsigned w) { return __uint_as_float(w << 16); }
; __device__ __forceinline__ float bfhi(unsigned w) { return __uint_as_float(w & 0xffff0000u); }
;     __device__ __forceinline__ void operator()(const f32x4 (&acc)[2][2][4][2], const Unit& u, int wr, int wc, int fr, int fq) const {
;         const int col0 = u.pn * 256 + wc * 32 + 8 * fq;
; #pragma unroll
;         for (int ai = 0; ai < 2; ++ai)
; #pragma unroll
;             for (int m = 0; m < 4; ++m) {
;                 const int row = u.pm * 256 + ai * 128 + wr * 64 + m * 16 + fr;
;                 if (row < MR) {
; #pragma unroll
;                     for (int bj = 0; bj < 2; ++bj) {
;                         const u32x4 gv = *(const u32x4*)(GATE + (size_t)row * 2048 + 1024 + col0 + bj * 128);
;                         const u32x4 tv = *(const u32x4*)(T + (size_t)row * DM + col0 + bj * 128);
;                         f32x4 a = (f32x4){bflo(tv.x), bfhi(tv.x), bflo(tv.y), bfhi(tv.y)}, b = (f32x4){bflo(tv.z), bfhi(tv.z), bflo(tv.w), bfhi(tv.w)};
;                         const f32x4 x = acc[ai][bj][m][0], y = acc[ai][bj][m][1];
;                         a[0] += x[0] * bflo(gv.x); a[1] += x[1] * bfhi(gv.x); a[2] += x[2] * bflo(gv.y); a[3] += x[3] * bfhi(gv.y);
;                         b[0] += y[0] * bflo(gv.z); b[1] += y[1] * bfhi(gv.z); b[2] += y[2] * bflo(gv.w); b[3] += y[3] * bfhi(gv.w);
;                         u32x4 w; w.x = pk2(a[0], a[1]); w.y = pk2(a[2], a[3]); w.z = pk2(b[0], b[1]); w.w = pk2(b[2], b[3]);
;                         *(u32x4*)(MG + (size_t)row * DM + col0 + bj * 128) = w;
;                     }
;                 }
;                 asm volatile("" ::: "memory");
;             }
;     }
.LBB0_2040:
	s_or_b64 exec, exec, s[26:27]
	v_add_u32_e32 v226, 0xb0, v146
	v_lshlrev_b32_e32 v226, 11, v226
	v_lshl_add_u64 v[228:229], s[8:9], 0, v[226:227]
	v_lshl_add_u64 v[228:229], v[228:229], 0, v[144:145]
	global_load_dwordx4 v[206:209], v[228:229], off
	global_load_dwordx4 v[214:217], v[228:229], off offset:256
	v_lshlrev_b32_e32 v226, 1, v226
	v_lshl_add_u64 v[228:229], s[10:11], 0, v[226:227]
	v_lshl_add_u64 v[228:229], v[228:229], 0, v[144:145]
	global_load_dwordx4 v[210:213], v[228:229], off offset:2048
	global_load_dwordx4 v[230:233], v[228:229], off offset:2304
	v_add_u32_e32 v32, 0xa0, v146
	v_cmp_gt_i32_e32 vcc, s61, v32
	s_and_saveexec_b64 s[26:27], vcc
	s_cbranch_execz .LBB0_2042
	v_ashrrev_i32_e32 v33, 31, v32
	v_lshlrev_b64 v[48:49], 11, v[32:33]
	v_lshlrev_b64 v[34:35], 12, v[32:33]
	v_lshl_add_u64 v[32:33], s[8:9], 0, v[48:49]
	v_lshl_add_u64 v[36:37], s[10:11], 0, v[34:35]
	v_lshl_add_u64 v[40:41], v[32:33], 0, v[144:145]
	v_lshl_add_u64 v[44:45], v[36:37], 0, v[144:145]
	s_nop 0
	s_nop 0
	v_lshl_add_u64 v[48:49], s[12:13], 0, v[48:49]
	v_lshl_add_u64 v[48:49], v[48:49], 0, v[144:145]
	s_waitcnt vmcnt(6)
	v_mov_b32_e32 v32, v190
	v_mov_b32_e32 v33, v191
	v_mov_b32_e32 v34, v192
	v_mov_b32_e32 v35, v193
	v_mov_b32_e32 v36, v194
	v_mov_b32_e32 v37, v195
	v_mov_b32_e32 v38, v196
	v_mov_b32_e32 v39, v197
	v_mov_b32_e32 v40, v198
	v_mov_b32_e32 v41, v199
	v_mov_b32_e32 v42, v200
	v_mov_b32_e32 v43, v201
	v_mov_b32_e32 v44, v202
	v_mov_b32_e32 v45, v203
	v_mov_b32_e32 v46, v204
	v_mov_b32_e32 v47, v205
	v_lshlrev_b32_e32 v52, 16, v36
	v_lshlrev_b32_e32 v50, 16, v32
	v_and_b32_e32 v51, 0xffff0000, v32
	v_and_b32_e32 v53, 0xffff0000, v36
	v_lshlrev_b32_e32 v32, 16, v33
	v_and_b32_e32 v33, 0xffff0000, v33
	v_lshlrev_b32_e32 v36, 16, v37
	v_and_b32_e32 v37, 0xffff0000, v37
	v_lshlrev_b32_e32 v54, 16, v34
	v_and_b32_e32 v55, 0xffff0000, v34
	v_lshlrev_b32_e32 v56, 16, v38
	v_and_b32_e32 v57, 0xffff0000, v38
	v_lshlrev_b32_e32 v34, 16, v35
	v_and_b32_e32 v35, 0xffff0000, v35
	v_lshlrev_b32_e32 v38, 16, v39
	v_and_b32_e32 v39, 0xffff0000, v39
	v_lshlrev_b32_e32 v58, 16, v40
	v_and_b32_e32 v59, 0xffff0000, v40
	v_lshlrev_b32_e32 v60, 16, v44
	v_and_b32_e32 v61, 0xffff0000, v44
	v_lshlrev_b32_e32 v40, 16, v41
	v_and_b32_e32 v41, 0xffff0000, v41
	v_lshlrev_b32_e32 v44, 16, v45
	v_and_b32_e32 v45, 0xffff0000, v45
	v_lshlrev_b32_e32 v62, 16, v42
	v_and_b32_e32 v63, 0xffff0000, v42
	v_lshlrev_b32_e32 v64, 16, v46
	v_and_b32_e32 v65, 0xffff0000, v46
	v_lshlrev_b32_e32 v42, 16, v43
	v_and_b32_e32 v43, 0xffff0000, v43
	v_lshlrev_b32_e32 v46, 16, v47
	v_and_b32_e32 v47, 0xffff0000, v47
	v_pk_fma_f32 v[28:29], v[28:29], v[52:53], v[50:51]
	v_pk_fma_f32 v[30:31], v[30:31], v[36:37], v[32:33]
	v_pk_fma_f32 v[24:25], v[24:25], v[56:57], v[54:55]
	v_pk_fma_f32 v[26:27], v[26:27], v[38:39], v[34:35]
	v_pk_fma_f32 v[20:21], v[20:21], v[60:61], v[58:59]
	v_pk_fma_f32 v[22:23], v[22:23], v[44:45], v[40:41]
	v_pk_fma_f32 v[32:33], v[16:17], v[64:65], v[62:63]
	v_pk_fma_f32 v[34:35], v[18:19], v[46:47], v[42:43]
	v_cvt_pk_bf16_f32 v16, v28, v29
	v_cvt_pk_bf16_f32 v17, v30, v31
	v_cvt_pk_bf16_f32 v18, v24, v25
	v_cvt_pk_bf16_f32 v19, v26, v27
	v_cvt_pk_bf16_f32 v20, v20, v21
	v_cvt_pk_bf16_f32 v21, v22, v23
	v_cvt_pk_bf16_f32 v22, v32, v33
	v_cvt_pk_bf16_f32 v23, v34, v35
	global_store_dwordx4 v[48:49], v[16:19], off
	global_store_dwordx4 v[48:49], v[20:23], off offset:256
.LBB0_2042:
	s_or_b64 exec, exec, s[26:27]
	v_add_u32_e32 v16, 0xb0, v146
	v_cmp_gt_i32_e32 vcc, s61, v16
	s_and_saveexec_b64 s[26:27], vcc
	s_cbranch_execz .LBB0_2044
	v_ashrrev_i32_e32 v17, 31, v16
	v_lshlrev_b64 v[32:33], 11, v[16:17]
	v_lshlrev_b64 v[18:19], 12, v[16:17]
	v_lshl_add_u64 v[16:17], s[8:9], 0, v[32:33]
	v_lshl_add_u64 v[20:21], s[10:11], 0, v[18:19]
	v_lshl_add_u64 v[24:25], v[16:17], 0, v[144:145]
	v_lshl_add_u64 v[28:29], v[20:21], 0, v[144:145]
	s_nop 0
	s_nop 0
	v_lshl_add_u64 v[32:33], s[12:13], 0, v[32:33]
	v_lshl_add_u64 v[32:33], v[32:33], 0, v[144:145]
	s_waitcnt vmcnt(2)
	v_mov_b32_e32 v16, v206
	v_mov_b32_e32 v17, v207
	v_mov_b32_e32 v18, v208
	v_mov_b32_e32 v19, v209
	v_mov_b32_e32 v20, v210
	v_mov_b32_e32 v21, v211
	v_mov_b32_e32 v22, v212
	v_mov_b32_e32 v23, v213
	v_mov_b32_e32 v24, v214
	v_mov_b32_e32 v25, v215
	v_mov_b32_e32 v26, v216
	v_mov_b32_e32 v27, v217
	v_mov_b32_e32 v28, v230
	v_mov_b32_e32 v29, v231
	v_mov_b32_e32 v30, v232
	v_mov_b32_e32 v31, v233
	v_lshlrev_b32_e32 v36, 16, v20
	v_lshlrev_b32_e32 v34, 16, v16
	v_and_b32_e32 v35, 0xffff0000, v16
	v_and_b32_e32 v37, 0xffff0000, v20
	v_lshlrev_b32_e32 v16, 16, v17
	v_and_b32_e32 v17, 0xffff0000, v17
	v_lshlrev_b32_e32 v20, 16, v21
	v_and_b32_e32 v21, 0xffff0000, v21
	v_lshlrev_b32_e32 v38, 16, v18
	v_and_b32_e32 v39, 0xffff0000, v18
	v_lshlrev_b32_e32 v40, 16, v22
	v_and_b32_e32 v41, 0xffff0000, v22
	v_lshlrev_b32_e32 v18, 16, v19
	v_and_b32_e32 v19, 0xffff0000, v19
	v_lshlrev_b32_e32 v22, 16, v23
	v_and_b32_e32 v23, 0xffff0000, v23
	v_lshlrev_b32_e32 v42, 16, v24
	v_and_b32_e32 v43, 0xffff0000, v24
	v_lshlrev_b32_e32 v44, 16, v28
	v_and_b32_e32 v45, 0xffff0000, v28
	v_lshlrev_b32_e32 v24, 16, v25
	v_and_b32_e32 v25, 0xffff0000, v25
	v_lshlrev_b32_e32 v28, 16, v29
	v_and_b32_e32 v29, 0xffff0000, v29
	v_lshlrev_b32_e32 v46, 16, v26
	v_and_b32_e32 v47, 0xffff0000, v26
	v_lshlrev_b32_e32 v48, 16, v30
	v_and_b32_e32 v49, 0xffff0000, v30
	v_lshlrev_b32_e32 v26, 16, v27
	v_and_b32_e32 v27, 0xffff0000, v27
	v_lshlrev_b32_e32 v30, 16, v31
	v_and_b32_e32 v31, 0xffff0000, v31
	v_pk_fma_f32 v[12:13], v[12:13], v[36:37], v[34:35]
	v_pk_fma_f32 v[14:15], v[14:15], v[20:21], v[16:17]
	v_pk_fma_f32 v[8:9], v[8:9], v[40:41], v[38:39]
	v_pk_fma_f32 v[10:11], v[10:11], v[22:23], v[18:19]
	v_pk_fma_f32 v[4:5], v[4:5], v[44:45], v[42:43]
	v_pk_fma_f32 v[6:7], v[6:7], v[28:29], v[24:25]
	v_pk_fma_f32 v[16:17], v[0:1], v[48:49], v[46:47]
	v_pk_fma_f32 v[18:19], v[2:3], v[30:31], v[26:27]
	v_cvt_pk_bf16_f32 v0, v12, v13
	v_cvt_pk_bf16_f32 v1, v14, v15
	v_cvt_pk_bf16_f32 v2, v8, v9
	v_cvt_pk_bf16_f32 v3, v10, v11
	v_cvt_pk_bf16_f32 v4, v4, v5
	v_cvt_pk_bf16_f32 v5, v6, v7
	v_cvt_pk_bf16_f32 v6, v16, v17
	v_cvt_pk_bf16_f32 v7, v18, v19
	global_store_dwordx4 v[32:33], v[0:3], off
	global_store_dwordx4 v[32:33], v[4:7], off offset:256
.LBB0_2044:
	s_or_b64 exec, exec, s[26:27]
	s_waitcnt vmcnt(0)
	s_andn2_b64 vcc, exec, s[2:3]
	s_mov_b64 s[2:3], -1
	s_cbranch_vccnz .LBB0_2017
	s_andn2_b64 vcc, exec, s[6:7]
	s_cbranch_vccnz .LBB0_2016
	s_barrier
	s_branch .LBB0_2016
